# unit heads: the runtime division by the row-group size (always 8 for M=32768) replaced by shift/mask in all six GEMM phases, on top of the K-loop edits
# speedup vs baseline: 1.0163x; 1.0163x over previous
;     __host__ __device__ bool next(int i, Unit& u) const {
;         const long L = (long)i * G + c; if (L >= nwg) return false;
;         int wgid = (int)L; { const int q = nwg / NXCD, r = nwg % NXCD, xcd = wgid % NXCD, off = wgid / NXCD; wgid = (xcd < r ? xcd * (q + 1) : r * (q + 1) + (xcd - r) * q) + off; }
;         const int nig = WGM * nN, gid = wgid / nig, fm = gid * WGM, gsz = (nM - fm) < WGM ? (nM - fm) : WGM;
;         u.pm = fm + ((wgid % nig) % gsz); u.pn = (wgid % nig) / gsz; return true;
.LBB0_325:
	s_ashr_i32 s4, s24, 3
	s_add_i32 s4, s26, s4
	s_ashr_i32 s5, s4, 31
	s_lshr_b32 s5, s5, 27
	s_add_i32 s5, s4, s5
	s_ashr_i32 s24, s5, 5
	s_lshl_b32 s25, s24, 3
	s_andn2_b32 s5, s5, 31
	s_sub_i32 s4, s4, s5
	s_lshr_b32 s24, s4, 3
	s_and_b32 s4, s4, 7
	s_add_i32 s26, s25, s4

;     __host__ __device__ bool next(int i, Unit& u) const {
;         const long L = (long)i * G + c; if (L >= nwg) return false;
;         int wgid = (int)L; { const int q = nwg / NXCD, r = nwg % NXCD, xcd = wgid % NXCD, off = wgid / NXCD; wgid = (xcd < r ? xcd * (q + 1) : r * (q + 1) + (xcd - r) * q) + off; }
;         const int nig = WGM * nN, gid = wgid / nig, fm = gid * WGM, gsz = (nM - fm) < WGM ? (nM - fm) : WGM;
;         u.pm = fm + ((wgid % nig) % gsz); u.pn = (wgid % nig) / gsz; return true;
.LBB0_443:
	s_add_i32 s45, s48, 1
	s_mul_i32 s5, s45, s68
	s_mul_hi_u32 s7, s45, s69
	s_add_i32 s7, s7, s5
	s_mul_i32 s5, s45, s69
	s_add_u32 s10, s5, s96
	s_addc_u32 s11, s7, s97
	v_mov_b64_e32 v[0:1], 0xb00
	v_cmp_gt_i64_e32 vcc, s[10:11], v[148:149]
	v_cmp_lt_i64_e64 s[8:9], s[10:11], v[0:1]
	s_cbranch_vccnz .LBB0_445
	s_ashr_i32 s4, s10, 31
	s_lshr_b32 s4, s4, 29
	s_add_i32 s4, s10, s4
	s_ashr_i32 s5, s4, 3
	s_and_b32 s4, s4, -8
	s_sub_i32 s4, s10, s4
	s_cmp_lt_i32 s4, 0
	s_cselect_b32 s6, s71, 0x160
	s_mul_i32 s4, s4, s6
	s_add_i32 s4, s4, s5
	s_mul_hi_i32 s5, s4, 0x2e8ba2e9
	s_lshr_b32 s6, s5, 31
	s_ashr_i32 s5, s5, 5
	s_add_i32 s5, s5, s6
	s_lshl_b32 s6, s5, 3
	s_mulk_i32 s5, 0xb0
	s_sub_i32 s5, s4, s5
	s_lshr_b32 s4, s5, 3
	s_and_b32 s5, s5, 7
	s_add_i32 s6, s6, s5

;     __host__ __device__ bool next(int i, Unit& u) const {
;         const long L = (long)i * G + c; if (L >= nwg) return false;
;         int wgid = (int)L; { const int q = nwg / NXCD, r = nwg % NXCD, xcd = wgid % NXCD, off = wgid / NXCD; wgid = (xcd < r ? xcd * (q + 1) : r * (q + 1) + (xcd - r) * q) + off; }
;         const int nig = WGM * nN, gid = wgid / nig, fm = gid * WGM, gsz = (nM - fm) < WGM ? (nM - fm) : WGM;
;         u.pm = fm + ((wgid % nig) % gsz); u.pn = (wgid % nig) / gsz; return true;
.LBB0_539:
	s_ashr_i32 s4, s6, 3
	s_add_i32 s4, s8, s4
	s_ashr_i32 s5, s4, 31
	s_lshr_b32 s5, s5, 27
	s_add_i32 s5, s4, s5
	s_ashr_i32 s6, s5, 5
	s_lshl_b32 s6, s6, 3
	s_andn2_b32 s5, s5, 31
	s_sub_i32 s4, s4, s5
	s_lshr_b32 s54, s4, 3
	s_and_b32 s4, s4, 7
	s_add_i32 s55, s6, s4

;     __host__ __device__ bool next(int i, Unit& u) const {
;         const long L = (long)i * G + c; if (L >= nwg) return false;
;         int wgid = (int)L; { const int q = nwg / NXCD, r = nwg % NXCD, xcd = wgid % NXCD, off = wgid / NXCD; wgid = (xcd < r ? xcd * (q + 1) : r * (q + 1) + (xcd - r) * q) + off; }
;         const int nig = WGM * nN, gid = wgid / nig, fm = gid * WGM, gsz = (nM - fm) < WGM ? (nM - fm) : WGM;
;         u.pm = fm + ((wgid % nig) % gsz); u.pn = (wgid % nig) / gsz; return true;
.LBB0_747:
	s_ashr_i32 s4, s13, 3
	s_add_i32 s4, s23, s4
	s_ashr_i32 s5, s4, 31
	s_lshr_b32 s5, s5, 26
	s_add_i32 s5, s4, s5
	s_ashr_i32 s13, s5, 6
	s_lshl_b32 s13, s13, 3
	s_andn2_b32 s5, s5, 63
	s_sub_i32 s4, s4, s5
	s_lshr_b32 s22, s4, 3
	s_and_b32 s4, s4, 7
	s_add_i32 s24, s13, s4

;     __host__ __device__ bool next(int i, Unit& u) const {
;         const long L = (long)i * G + c; if (L >= nwg) return false;
;         int wgid = (int)L; { const int q = nwg / NXCD, r = nwg % NXCD, xcd = wgid % NXCD, off = wgid / NXCD; wgid = (xcd < r ? xcd * (q + 1) : r * (q + 1) + (xcd - r) * q) + off; }
;         const int nig = WGM * nN, gid = wgid / nig, fm = gid * WGM, gsz = (nM - fm) < WGM ? (nM - fm) : WGM;
;         u.pm = fm + ((wgid % nig) % gsz); u.pn = (wgid % nig) / gsz; return true;
.LBB0_789:
	s_add_i32 s43, s47, 1
	s_mul_i32 s4, s43, s68
	s_mul_hi_u32 s5, s43, s69
	s_add_i32 s5, s5, s4
	s_mul_i32 s4, s43, s69
	s_add_u32 s4, s4, s96
	s_addc_u32 s5, s5, s97
	v_cmp_gt_i64_e32 vcc, s[4:5], v[160:161]
	v_cmp_lt_i64_e64 s[8:9], s[4:5], v[158:159]
	s_cbranch_vccnz .LBB0_791
	s_ashr_i32 s5, s4, 31
	s_lshr_b32 s5, s5, 29
	s_add_i32 s5, s4, s5
	s_ashr_i32 s14, s5, 3
	s_and_b32 s5, s5, -8
	s_sub_i32 s4, s4, s5
	s_cmp_lt_i32 s4, 0
	s_movk_i32 s5, 0x61
	s_cselect_b32 s5, s5, 0x60
	s_mul_i32 s4, s4, s5
	s_add_i32 s4, s4, s14
	s_mul_hi_i32 s5, s4, 0x2aaaaaab
	s_lshr_b32 s14, s5, 31
	s_ashr_i32 s5, s5, 3
	s_add_i32 s5, s5, s14
	s_lshl_b32 s15, s5, 3
	s_mul_i32 s5, s5, 48
	s_sub_i32 s4, s4, s5
	s_lshr_b32 s14, s4, 3
	s_and_b32 s4, s4, 7
	s_add_i32 s16, s15, s4

;     __host__ __device__ bool next(int i, Unit& u) const {
;         const long L = (long)i * G + c; if (L >= nwg) return false;
;         int wgid = (int)L; { const int q = nwg / NXCD, r = nwg % NXCD, xcd = wgid % NXCD, off = wgid / NXCD; wgid = (xcd < r ? xcd * (q + 1) : r * (q + 1) + (xcd - r) * q) + off; }
;         const int nig = WGM * nN, gid = wgid / nig, fm = gid * WGM, gsz = (nM - fm) < WGM ? (nM - fm) : WGM;
;         u.pm = fm + ((wgid % nig) % gsz); u.pn = (wgid % nig) / gsz; return true;
.LBB0_1040:
	s_ashr_i32 s4, s20, 3
	s_add_i32 s4, s22, s4
	s_ashr_i32 s5, s4, 31
	s_lshr_b32 s5, s5, 27
	s_add_i32 s5, s4, s5
	s_ashr_i32 s20, s5, 5
	s_lshl_b32 s21, s20, 3
	s_andn2_b32 s5, s5, 31
	s_sub_i32 s4, s4, s5
	s_lshr_b32 s20, s4, 3
	s_and_b32 s4, s4, 7
	s_add_i32 s22, s21, s4
